# k39 + last grid barrier (FF2 -> gate) as row-panel rendezvous: 4 arrivals per panel, only the sample-row WGs wait for the whole grid
# speedup vs baseline: 1.0667x; 1.0537x over previous
.LBB0_1000:
	s_or_b64 exec, exec, s[10:11]
	s_waitcnt lgkmcnt(0)
	s_barrier
	s_waitcnt lgkmcnt(0)
	v_lshl_add_u64 v[202:203], v[200:201], 2, s[34:35]
	global_load_dwordx4 v[196:199], v[202:203], off
	global_load_dwordx4 v[192:195], v[202:203], off offset:16
	global_load_dwordx4 v[236:239], v[202:203], off offset:512
	global_load_dwordx4 v[240:243], v[202:203], off offset:528
	v_lshl_add_u32 v206, v204, 2, 0
	ds_read_b32 v224, v206 offset:8192
	s_waitcnt vmcnt(2)
	v_lshlrev_b32_e32 v208, 16, v188
	v_and_b32_e32 v209, 0xffff0000, v188
	v_lshlrev_b32_e32 v210, 16, v189
	v_and_b32_e32 v211, 0xffff0000, v189
	s_waitcnt lgkmcnt(0)
	v_pk_mul_f32 v[126:127], v[126:127], v[224:225] op_sel_hi:[1,0]
	v_pk_mul_f32 v[124:125], v[124:125], v[224:225] op_sel_hi:[1,0]
	v_lshlrev_b32_e32 v212, 16, v190
	v_and_b32_e32 v213, 0xffff0000, v190
	v_lshlrev_b32_e32 v190, 16, v191
	v_and_b32_e32 v191, 0xffff0000, v191
	v_pk_mul_f32 v[122:123], v[122:123], v[224:225] op_sel_hi:[1,0]
	v_pk_mul_f32 v[120:121], v[120:121], v[224:225] op_sel_hi:[1,0]
	v_add_u32_e32 v204, s26, v204
	v_add_u32_e32 v226, 16, v204
	s_add_u32 s8, s18, 0x24800000
	v_ashrrev_i32_e32 v205, 31, v204
	v_ashrrev_i32_e32 v227, 31, v226
	s_addc_u32 s9, s19, 0
	v_lshlrev_b64 v[228:229], 11, v[204:205]
	v_lshlrev_b64 v[226:227], 11, v[226:227]
	v_lshlrev_b64 v[188:189], 1, v[200:201]
	v_lshl_add_u64 v[228:229], s[8:9], 0, v[228:229]
	v_lshlrev_b32_e32 v200, 16, v184
	v_and_b32_e32 v201, 0xffff0000, v184
	v_lshlrev_b32_e32 v184, 16, v185
	v_and_b32_e32 v185, 0xffff0000, v185
	v_lshlrev_b32_e32 v214, 16, v186
	v_and_b32_e32 v215, 0xffff0000, v186
	v_lshlrev_b32_e32 v186, 16, v187
	v_and_b32_e32 v187, 0xffff0000, v187
	v_lshlrev_b32_e32 v216, 16, v180
	v_and_b32_e32 v217, 0xffff0000, v180
	v_lshlrev_b32_e32 v180, 16, v181
	v_and_b32_e32 v181, 0xffff0000, v181
	v_lshlrev_b32_e32 v218, 16, v182
	v_and_b32_e32 v219, 0xffff0000, v182
	v_lshlrev_b32_e32 v182, 16, v183
	v_and_b32_e32 v183, 0xffff0000, v183
	v_lshlrev_b32_e32 v220, 16, v176
	v_and_b32_e32 v221, 0xffff0000, v176
	v_lshlrev_b32_e32 v222, 16, v178
	v_and_b32_e32 v223, 0xffff0000, v178
	v_lshlrev_b32_e32 v176, 16, v177
	v_and_b32_e32 v177, 0xffff0000, v177
	v_lshlrev_b32_e32 v178, 16, v179
	v_and_b32_e32 v179, 0xffff0000, v179
	v_pk_fma_f32 v[124:125], v[196:197], v[124:125], v[208:209]
	v_pk_fma_f32 v[126:127], v[198:199], v[126:127], v[210:211]
	v_pk_fma_f32 v[120:121], v[192:193], v[120:121], v[212:213]
	v_pk_fma_f32 v[122:123], v[194:195], v[122:123], v[190:191]
	v_cvt_pk_bf16_f32 v124, v124, v125
	v_cvt_pk_bf16_f32 v125, v126, v127
	v_cvt_pk_bf16_f32 v126, v120, v121
	v_lshl_add_u64 v[120:121], s[8:9], 0, v[226:227]
	v_cvt_pk_bf16_f32 v127, v122, v123
	ds_read_b32 v190, v206 offset:8256
	v_lshl_add_u64 v[122:123], v[228:229], 0, v[188:189]
	v_lshl_add_u64 v[120:121], v[120:121], 0, v[188:189]
	global_store_dwordx4 v[122:123], v[124:127], off sc1
	s_waitcnt lgkmcnt(0)
	v_pk_mul_f32 v[118:119], v[118:119], v[190:191] op_sel_hi:[1,0]
	v_pk_mul_f32 v[116:117], v[116:117], v[190:191] op_sel_hi:[1,0]
	v_pk_mul_f32 v[114:115], v[114:115], v[190:191] op_sel_hi:[1,0]
	v_pk_mul_f32 v[112:113], v[112:113], v[190:191] op_sel_hi:[1,0]
	v_pk_fma_f32 v[116:117], v[196:197], v[116:117], v[200:201]
	v_pk_fma_f32 v[118:119], v[198:199], v[118:119], v[184:185]
	v_pk_fma_f32 v[124:125], v[192:193], v[112:113], v[214:215]
	v_pk_fma_f32 v[126:127], v[194:195], v[114:115], v[186:187]
	v_cvt_pk_bf16_f32 v112, v116, v117
	v_cvt_pk_bf16_f32 v113, v118, v119
	v_cvt_pk_bf16_f32 v114, v124, v125
	v_add_u32_e32 v116, 48, v204
	v_cvt_pk_bf16_f32 v115, v126, v127
	global_store_dwordx4 v[120:121], v[112:115], off sc1
	ds_read_b32 v112, v206 offset:8320
	v_ashrrev_i32_e32 v117, 31, v116
	v_add_u32_e32 v114, 32, v204
	v_ashrrev_i32_e32 v115, 31, v114
	s_waitcnt lgkmcnt(0)
	v_pk_mul_f32 v[110:111], v[110:111], v[112:113] op_sel_hi:[1,0]
	v_pk_mul_f32 v[108:109], v[108:109], v[112:113] op_sel_hi:[1,0]
	v_pk_mul_f32 v[106:107], v[106:107], v[112:113] op_sel_hi:[1,0]
	v_pk_mul_f32 v[104:105], v[104:105], v[112:113] op_sel_hi:[1,0]
	v_pk_fma_f32 v[108:109], v[196:197], v[108:109], v[216:217]
	v_pk_fma_f32 v[110:111], v[198:199], v[110:111], v[180:181]
	v_pk_fma_f32 v[104:105], v[192:193], v[104:105], v[218:219]
	v_pk_fma_f32 v[112:113], v[194:195], v[106:107], v[182:183]
	v_cvt_pk_bf16_f32 v106, v108, v109
	v_cvt_pk_bf16_f32 v107, v110, v111
	v_cvt_pk_bf16_f32 v108, v104, v105
	v_lshlrev_b64 v[104:105], 11, v[114:115]
	v_cvt_pk_bf16_f32 v109, v112, v113
	ds_read_b32 v110, v206 offset:8384
	v_lshl_add_u64 v[104:105], s[8:9], 0, v[104:105]
	v_lshl_add_u64 v[104:105], v[104:105], 0, v[188:189]
	global_store_dwordx4 v[104:105], v[106:109], off sc1
	s_waitcnt lgkmcnt(0)
	v_pk_mul_f32 v[100:101], v[100:101], v[110:111] op_sel_hi:[1,0]
	v_pk_mul_f32 v[96:97], v[96:97], v[110:111] op_sel_hi:[1,0]
	v_pk_mul_f32 v[102:103], v[102:103], v[110:111] op_sel_hi:[1,0]
	v_pk_fma_f32 v[100:101], v[196:197], v[100:101], v[220:221]
	v_pk_mul_f32 v[98:99], v[98:99], v[110:111] op_sel_hi:[1,0]
	v_pk_fma_f32 v[96:97], v[192:193], v[96:97], v[222:223]
	v_pk_fma_f32 v[102:103], v[198:199], v[102:103], v[176:177]
	v_pk_fma_f32 v[106:107], v[194:195], v[98:99], v[178:179]
	v_cvt_pk_bf16_f32 v98, v100, v101
	v_cvt_pk_bf16_f32 v99, v102, v103
	v_cvt_pk_bf16_f32 v100, v96, v97
	v_lshlrev_b64 v[96:97], 11, v[116:117]
	v_lshl_add_u64 v[96:97], s[8:9], 0, v[96:97]
	v_lshl_add_u64 v[96:97], v[96:97], 0, v[188:189]
	v_cvt_pk_bf16_f32 v101, v106, v107
	global_store_dwordx4 v[96:97], v[98:101], off sc1
	ds_read_b32 v98, v206 offset:8704
	v_lshlrev_b32_e32 v102, 16, v172
	v_add_u32_e32 v100, 0x80, v204
	v_and_b32_e32 v103, 0xffff0000, v172
	v_lshlrev_b32_e32 v108, 16, v174
	v_and_b32_e32 v109, 0xffff0000, v174
	s_waitcnt lgkmcnt(0)
	v_pk_mul_f32 v[92:93], v[92:93], v[98:99] op_sel_hi:[1,0]
	v_pk_mul_f32 v[88:89], v[88:89], v[98:99] op_sel_hi:[1,0]
	v_ashrrev_i32_e32 v101, 31, v100
	v_lshlrev_b32_e32 v106, 16, v173
	v_and_b32_e32 v107, 0xffff0000, v173
	v_lshlrev_b32_e32 v110, 16, v175
	v_and_b32_e32 v111, 0xffff0000, v175
	v_pk_mul_f32 v[94:95], v[94:95], v[98:99] op_sel_hi:[1,0]
	v_pk_fma_f32 v[92:93], v[196:197], v[92:93], v[102:103]
	v_pk_mul_f32 v[90:91], v[90:91], v[98:99] op_sel_hi:[1,0]
	v_pk_fma_f32 v[88:89], v[192:193], v[88:89], v[108:109]
	v_pk_fma_f32 v[94:95], v[198:199], v[94:95], v[106:107]
	v_pk_fma_f32 v[98:99], v[194:195], v[90:91], v[110:111]
	v_cvt_pk_bf16_f32 v90, v92, v93
	v_cvt_pk_bf16_f32 v91, v94, v95
	v_cvt_pk_bf16_f32 v92, v88, v89
	v_lshlrev_b64 v[88:89], 11, v[100:101]
	v_lshl_add_u64 v[88:89], s[8:9], 0, v[88:89]
	v_lshl_add_u64 v[88:89], v[88:89], 0, v[188:189]
	v_cvt_pk_bf16_f32 v93, v98, v99
	global_store_dwordx4 v[88:89], v[90:93], off sc1
	ds_read_b32 v90, v206 offset:8768
	v_lshlrev_b32_e32 v94, 16, v168
	v_add_u32_e32 v92, 0x90, v204
	v_and_b32_e32 v95, 0xffff0000, v168
	v_lshlrev_b32_e32 v100, 16, v170
	v_and_b32_e32 v101, 0xffff0000, v170
	s_waitcnt lgkmcnt(0)
	v_pk_mul_f32 v[84:85], v[84:85], v[90:91] op_sel_hi:[1,0]
	v_pk_mul_f32 v[80:81], v[80:81], v[90:91] op_sel_hi:[1,0]
	v_ashrrev_i32_e32 v93, 31, v92
	v_lshlrev_b32_e32 v98, 16, v169
	v_and_b32_e32 v99, 0xffff0000, v169
	v_lshlrev_b32_e32 v102, 16, v171
	v_and_b32_e32 v103, 0xffff0000, v171
	v_pk_mul_f32 v[86:87], v[86:87], v[90:91] op_sel_hi:[1,0]
	v_pk_fma_f32 v[84:85], v[196:197], v[84:85], v[94:95]
	v_pk_mul_f32 v[82:83], v[82:83], v[90:91] op_sel_hi:[1,0]
	v_pk_fma_f32 v[80:81], v[192:193], v[80:81], v[100:101]
	v_pk_fma_f32 v[86:87], v[198:199], v[86:87], v[98:99]
	v_pk_fma_f32 v[90:91], v[194:195], v[82:83], v[102:103]
	v_cvt_pk_bf16_f32 v82, v84, v85
	v_cvt_pk_bf16_f32 v83, v86, v87
	v_cvt_pk_bf16_f32 v84, v80, v81
	v_lshlrev_b64 v[80:81], 11, v[92:93]
	v_lshl_add_u64 v[80:81], s[8:9], 0, v[80:81]
	v_lshl_add_u64 v[80:81], v[80:81], 0, v[188:189]
	v_cvt_pk_bf16_f32 v85, v90, v91
	global_store_dwordx4 v[80:81], v[82:85], off sc1
	ds_read_b32 v82, v206 offset:8832
	v_lshlrev_b32_e32 v86, 16, v164
	v_add_u32_e32 v84, 0xa0, v204
	v_and_b32_e32 v87, 0xffff0000, v164
	v_lshlrev_b32_e32 v92, 16, v166
	v_and_b32_e32 v93, 0xffff0000, v166
	s_waitcnt lgkmcnt(0)
	v_pk_mul_f32 v[76:77], v[76:77], v[82:83] op_sel_hi:[1,0]
	v_pk_mul_f32 v[72:73], v[72:73], v[82:83] op_sel_hi:[1,0]
	v_ashrrev_i32_e32 v85, 31, v84
	v_lshlrev_b32_e32 v90, 16, v165
	v_and_b32_e32 v91, 0xffff0000, v165
	v_lshlrev_b32_e32 v94, 16, v167
	v_and_b32_e32 v95, 0xffff0000, v167
	v_pk_mul_f32 v[78:79], v[78:79], v[82:83] op_sel_hi:[1,0]
	v_pk_fma_f32 v[76:77], v[196:197], v[76:77], v[86:87]
	v_pk_mul_f32 v[74:75], v[74:75], v[82:83] op_sel_hi:[1,0]
	v_pk_fma_f32 v[72:73], v[192:193], v[72:73], v[92:93]
	v_pk_fma_f32 v[78:79], v[198:199], v[78:79], v[90:91]
	v_pk_fma_f32 v[82:83], v[194:195], v[74:75], v[94:95]
	v_cvt_pk_bf16_f32 v74, v76, v77
	v_cvt_pk_bf16_f32 v75, v78, v79
	v_cvt_pk_bf16_f32 v76, v72, v73
	v_lshlrev_b64 v[72:73], 11, v[84:85]
	v_lshl_add_u64 v[72:73], s[8:9], 0, v[72:73]
	v_lshl_add_u64 v[72:73], v[72:73], 0, v[188:189]
	v_cvt_pk_bf16_f32 v77, v82, v83
	global_store_dwordx4 v[72:73], v[74:77], off sc1
	ds_read_b32 v74, v206 offset:8896
	v_lshlrev_b32_e32 v78, 16, v160
	v_add_u32_e32 v76, 0xb0, v204
	v_and_b32_e32 v79, 0xffff0000, v160
	v_ashrrev_i32_e32 v77, 31, v76
	s_waitcnt lgkmcnt(0)
	v_pk_mul_f32 v[68:69], v[68:69], v[74:75] op_sel_hi:[1,0]
	v_lshlrev_b32_e32 v84, 16, v162
	v_and_b32_e32 v85, 0xffff0000, v162
	v_pk_fma_f32 v[68:69], v[196:197], v[68:69], v[78:79]
	v_pk_mul_f32 v[64:65], v[64:65], v[74:75] op_sel_hi:[1,0]
	v_pk_mul_f32 v[70:71], v[70:71], v[74:75] op_sel_hi:[1,0]
	v_pk_mul_f32 v[66:67], v[66:67], v[74:75] op_sel_hi:[1,0]
	v_pk_fma_f32 v[74:75], v[192:193], v[64:65], v[84:85]
	v_cvt_pk_bf16_f32 v64, v68, v69
	v_lshlrev_b64 v[68:69], 11, v[76:77]
	v_lshlrev_b32_e32 v82, 16, v161
	v_and_b32_e32 v83, 0xffff0000, v161
	v_lshlrev_b32_e32 v86, 16, v163
	v_and_b32_e32 v87, 0xffff0000, v163
	v_lshl_add_u64 v[68:69], s[8:9], 0, v[68:69]
	v_pk_fma_f32 v[70:71], v[198:199], v[70:71], v[82:83]
	v_pk_fma_f32 v[78:79], v[194:195], v[66:67], v[86:87]
	v_cvt_pk_bf16_f32 v65, v70, v71
	v_cvt_pk_bf16_f32 v66, v74, v75
	v_lshl_add_u64 v[74:75], v[68:69], 0, v[188:189]
	v_cvt_pk_bf16_f32 v67, v78, v79
	global_store_dwordx4 v[74:75], v[64:67], off sc1
	ds_read_b32 v76, v206 offset:8192
	v_lshlrev_b32_e32 v78, 16, v156
	v_and_b32_e32 v79, 0xffff0000, v156
	v_lshlrev_b32_e32 v84, 16, v158
	v_and_b32_e32 v85, 0xffff0000, v158
	s_waitcnt lgkmcnt(0)
	v_pk_mul_f32 v[60:61], v[60:61], v[76:77] op_sel_hi:[1,0]
	v_pk_mul_f32 v[56:57], v[56:57], v[76:77] op_sel_hi:[1,0]
	v_lshlrev_b32_e32 v82, 16, v157
	v_and_b32_e32 v83, 0xffff0000, v157
	v_lshlrev_b32_e32 v86, 16, v159
	v_and_b32_e32 v87, 0xffff0000, v159
	v_pk_mul_f32 v[62:63], v[62:63], v[76:77] op_sel_hi:[1,0]
	v_pk_mul_f32 v[58:59], v[58:59], v[76:77] op_sel_hi:[1,0]
	s_waitcnt vmcnt(8)
	v_pk_fma_f32 v[60:61], v[236:237], v[60:61], v[78:79]
	v_pk_fma_f32 v[76:77], v[240:241], v[56:57], v[84:85]
	v_cvt_pk_bf16_f32 v56, v60, v61
	v_pk_fma_f32 v[62:63], v[238:239], v[62:63], v[82:83]
	v_pk_fma_f32 v[78:79], v[242:243], v[58:59], v[86:87]
	v_cvt_pk_bf16_f32 v57, v62, v63
	v_cvt_pk_bf16_f32 v58, v76, v77
	v_lshlrev_b32_e32 v60, 16, v153
	v_cvt_pk_bf16_f32 v59, v78, v79
	global_store_dwordx4 v[122:123], v[56:59], off offset:256 sc1
	ds_read_b32 v56, v206 offset:8256
	v_and_b32_e32 v61, 0xffff0000, v153
	v_lshlrev_b32_e32 v58, 16, v152
	v_and_b32_e32 v59, 0xffff0000, v152
	v_lshlrev_b32_e32 v62, 16, v154
	v_and_b32_e32 v63, 0xffff0000, v154
	v_lshlrev_b32_e32 v76, 16, v155
	v_and_b32_e32 v77, 0xffff0000, v155
	s_waitcnt lgkmcnt(0)
	v_pk_mul_f32 v[54:55], v[54:55], v[56:57] op_sel_hi:[1,0]
	v_pk_mul_f32 v[52:53], v[52:53], v[56:57] op_sel_hi:[1,0]
	v_pk_mul_f32 v[50:51], v[50:51], v[56:57] op_sel_hi:[1,0]
	v_pk_mul_f32 v[48:49], v[48:49], v[56:57] op_sel_hi:[1,0]
	v_pk_fma_f32 v[52:53], v[236:237], v[52:53], v[58:59]
	v_pk_fma_f32 v[54:55], v[238:239], v[54:55], v[60:61]
	v_pk_fma_f32 v[56:57], v[240:241], v[48:49], v[62:63]
	v_pk_fma_f32 v[58:59], v[242:243], v[50:51], v[76:77]
	v_cvt_pk_bf16_f32 v48, v52, v53
	v_cvt_pk_bf16_f32 v49, v54, v55
	v_cvt_pk_bf16_f32 v50, v56, v57
	v_lshlrev_b32_e32 v54, 16, v150
	v_cvt_pk_bf16_f32 v51, v58, v59
	global_store_dwordx4 v[120:121], v[48:51], off offset:256 sc1
	ds_read_b32 v48, v206 offset:8320
	v_and_b32_e32 v55, 0xffff0000, v150
	v_lshlrev_b32_e32 v50, 16, v148
	v_and_b32_e32 v51, 0xffff0000, v148
	v_lshlrev_b32_e32 v52, 16, v149
	s_waitcnt lgkmcnt(0)
	v_pk_mul_f32 v[44:45], v[44:45], v[48:49] op_sel_hi:[1,0]
	v_pk_mul_f32 v[40:41], v[40:41], v[48:49] op_sel_hi:[1,0]
	v_and_b32_e32 v53, 0xffff0000, v149
	v_lshlrev_b32_e32 v56, 16, v151
	v_and_b32_e32 v57, 0xffff0000, v151
	v_pk_mul_f32 v[46:47], v[46:47], v[48:49] op_sel_hi:[1,0]
	v_pk_fma_f32 v[44:45], v[236:237], v[44:45], v[50:51]
	v_pk_mul_f32 v[42:43], v[42:43], v[48:49] op_sel_hi:[1,0]
	v_pk_fma_f32 v[48:49], v[240:241], v[40:41], v[54:55]
	v_cvt_pk_bf16_f32 v40, v44, v45
	v_pk_fma_f32 v[46:47], v[238:239], v[46:47], v[52:53]
	v_pk_fma_f32 v[50:51], v[242:243], v[42:43], v[56:57]
	v_cvt_pk_bf16_f32 v41, v46, v47
	v_cvt_pk_bf16_f32 v42, v48, v49
	v_lshlrev_b32_e32 v44, 16, v145
	v_cvt_pk_bf16_f32 v43, v50, v51
	global_store_dwordx4 v[104:105], v[40:43], off offset:256 sc1
	ds_read_b32 v40, v206 offset:8384
	v_and_b32_e32 v45, 0xffff0000, v145
	v_lshlrev_b32_e32 v42, 16, v144
	v_and_b32_e32 v43, 0xffff0000, v144
	v_lshlrev_b32_e32 v46, 16, v146
	v_and_b32_e32 v47, 0xffff0000, v146
	v_lshlrev_b32_e32 v48, 16, v147
	v_and_b32_e32 v49, 0xffff0000, v147
	s_waitcnt lgkmcnt(0)
	v_pk_mul_f32 v[38:39], v[38:39], v[40:41] op_sel_hi:[1,0]
	v_pk_mul_f32 v[36:37], v[36:37], v[40:41] op_sel_hi:[1,0]
	v_pk_mul_f32 v[34:35], v[34:35], v[40:41] op_sel_hi:[1,0]
	v_pk_mul_f32 v[32:33], v[32:33], v[40:41] op_sel_hi:[1,0]
	v_pk_fma_f32 v[36:37], v[236:237], v[36:37], v[42:43]
	v_pk_fma_f32 v[38:39], v[238:239], v[38:39], v[44:45]
	v_pk_fma_f32 v[40:41], v[240:241], v[32:33], v[46:47]
	v_pk_fma_f32 v[42:43], v[242:243], v[34:35], v[48:49]
	v_cvt_pk_bf16_f32 v32, v36, v37
	v_cvt_pk_bf16_f32 v33, v38, v39
	v_cvt_pk_bf16_f32 v34, v40, v41
	v_lshlrev_b32_e32 v38, 16, v142
	v_cvt_pk_bf16_f32 v35, v42, v43
	global_store_dwordx4 v[96:97], v[32:35], off offset:256 sc1
	ds_read_b32 v32, v206 offset:8704
	v_and_b32_e32 v39, 0xffff0000, v142
	v_lshlrev_b32_e32 v34, 16, v140
	v_and_b32_e32 v35, 0xffff0000, v140
	v_lshlrev_b32_e32 v36, 16, v141
	s_waitcnt lgkmcnt(0)
	v_pk_mul_f32 v[28:29], v[28:29], v[32:33] op_sel_hi:[1,0]
	v_pk_mul_f32 v[24:25], v[24:25], v[32:33] op_sel_hi:[1,0]
	v_and_b32_e32 v37, 0xffff0000, v141
	v_lshlrev_b32_e32 v40, 16, v143
	v_and_b32_e32 v41, 0xffff0000, v143
	v_pk_mul_f32 v[30:31], v[30:31], v[32:33] op_sel_hi:[1,0]
	v_pk_fma_f32 v[28:29], v[236:237], v[28:29], v[34:35]
	v_pk_mul_f32 v[26:27], v[26:27], v[32:33] op_sel_hi:[1,0]
	v_pk_fma_f32 v[32:33], v[240:241], v[24:25], v[38:39]
	v_cvt_pk_bf16_f32 v24, v28, v29
	v_pk_fma_f32 v[30:31], v[238:239], v[30:31], v[36:37]
	v_pk_fma_f32 v[34:35], v[242:243], v[26:27], v[40:41]
	v_cvt_pk_bf16_f32 v25, v30, v31
	v_cvt_pk_bf16_f32 v26, v32, v33
	v_lshlrev_b32_e32 v28, 16, v137
	v_cvt_pk_bf16_f32 v27, v34, v35
	global_store_dwordx4 v[88:89], v[24:27], off offset:256 sc1
	ds_read_b32 v24, v206 offset:8768
	v_and_b32_e32 v29, 0xffff0000, v137
	v_lshlrev_b32_e32 v26, 16, v136
	v_and_b32_e32 v27, 0xffff0000, v136
	v_lshlrev_b32_e32 v30, 16, v138
	v_and_b32_e32 v31, 0xffff0000, v138
	v_lshlrev_b32_e32 v32, 16, v139
	v_and_b32_e32 v33, 0xffff0000, v139
	s_waitcnt lgkmcnt(0)
	v_pk_mul_f32 v[22:23], v[22:23], v[24:25] op_sel_hi:[1,0]
	v_pk_mul_f32 v[20:21], v[20:21], v[24:25] op_sel_hi:[1,0]
	v_pk_mul_f32 v[18:19], v[18:19], v[24:25] op_sel_hi:[1,0]
	v_pk_mul_f32 v[16:17], v[16:17], v[24:25] op_sel_hi:[1,0]
	v_pk_fma_f32 v[20:21], v[236:237], v[20:21], v[26:27]
	v_pk_fma_f32 v[22:23], v[238:239], v[22:23], v[28:29]
	v_pk_fma_f32 v[24:25], v[240:241], v[16:17], v[30:31]
	v_pk_fma_f32 v[26:27], v[242:243], v[18:19], v[32:33]
	v_cvt_pk_bf16_f32 v16, v20, v21
	v_cvt_pk_bf16_f32 v17, v22, v23
	v_cvt_pk_bf16_f32 v18, v24, v25
	v_lshlrev_b32_e32 v22, 16, v134
	v_cvt_pk_bf16_f32 v19, v26, v27
	global_store_dwordx4 v[80:81], v[16:19], off offset:256 sc1
	ds_read_b32 v16, v206 offset:8832
	v_and_b32_e32 v23, 0xffff0000, v134
	v_lshlrev_b32_e32 v18, 16, v132
	v_and_b32_e32 v19, 0xffff0000, v132
	v_lshlrev_b32_e32 v20, 16, v133
	s_waitcnt lgkmcnt(0)
	v_pk_mul_f32 v[12:13], v[12:13], v[16:17] op_sel_hi:[1,0]
	v_pk_mul_f32 v[8:9], v[8:9], v[16:17] op_sel_hi:[1,0]
	v_and_b32_e32 v21, 0xffff0000, v133
	v_lshlrev_b32_e32 v24, 16, v135
	v_and_b32_e32 v25, 0xffff0000, v135
	v_pk_mul_f32 v[14:15], v[14:15], v[16:17] op_sel_hi:[1,0]
	v_pk_fma_f32 v[12:13], v[236:237], v[12:13], v[18:19]
	v_pk_mul_f32 v[10:11], v[10:11], v[16:17] op_sel_hi:[1,0]
	v_pk_fma_f32 v[16:17], v[240:241], v[8:9], v[22:23]
	v_cvt_pk_bf16_f32 v8, v12, v13
	v_pk_fma_f32 v[14:15], v[238:239], v[14:15], v[20:21]
	v_pk_fma_f32 v[18:19], v[242:243], v[10:11], v[24:25]
	v_cvt_pk_bf16_f32 v9, v14, v15
	v_cvt_pk_bf16_f32 v10, v16, v17
	v_lshlrev_b32_e32 v12, 16, v129
	v_cvt_pk_bf16_f32 v11, v18, v19
	global_store_dwordx4 v[72:73], v[8:11], off offset:256 sc1
	ds_read_b32 v8, v206 offset:8896
	v_and_b32_e32 v13, 0xffff0000, v129
	v_lshlrev_b32_e32 v10, 16, v128
	v_and_b32_e32 v11, 0xffff0000, v128
	v_lshlrev_b32_e32 v14, 16, v130
	v_and_b32_e32 v15, 0xffff0000, v130
	v_lshlrev_b32_e32 v16, 16, v131
	v_and_b32_e32 v17, 0xffff0000, v131
	s_waitcnt lgkmcnt(0)
	v_pk_mul_f32 v[6:7], v[6:7], v[8:9] op_sel_hi:[1,0]
	v_pk_mul_f32 v[4:5], v[4:5], v[8:9] op_sel_hi:[1,0]
	v_pk_mul_f32 v[2:3], v[2:3], v[8:9] op_sel_hi:[1,0]
	v_pk_mul_f32 v[0:1], v[0:1], v[8:9] op_sel_hi:[1,0]
	v_pk_fma_f32 v[4:5], v[236:237], v[4:5], v[10:11]
	v_pk_fma_f32 v[6:7], v[238:239], v[6:7], v[12:13]
	v_pk_fma_f32 v[8:9], v[240:241], v[0:1], v[14:15]
	v_pk_fma_f32 v[10:11], v[242:243], v[2:3], v[16:17]
	v_cvt_pk_bf16_f32 v0, v4, v5
	v_cvt_pk_bf16_f32 v1, v6, v7
	v_cvt_pk_bf16_f32 v2, v8, v9
	s_nop 0
	v_cvt_pk_bf16_f32 v3, v10, v11
	global_store_dwordx4 v[74:75], v[0:3], off offset:256 sc1
